# grid barriers: one early L2 write-back per XCD issued by the 26th-of-32 arriver (pre-flush) so the leader flush has less dirty data
# speedup vs baseline: 1.0002x; 1.0002x over previous
; __device__ __forceinline__ unsigned xb_ld(unsigned* p)              { return __hip_atomic_load(p, __ATOMIC_RELAXED, __HIP_MEMORY_SCOPE_AGENT); }
; __device__ __forceinline__ unsigned xb_add(unsigned* p, unsigned v) { return __hip_atomic_fetch_add(p, v, __ATOMIC_RELAXED, __HIP_MEMORY_SCOPE_AGENT); }
; #define XB_SPIN(cond, bar) do { unsigned _sp = 0; while (cond) { __builtin_amdgcn_s_sleep(1); \
;     if ((++_sp & 255u) == 0u) { if (xb_ld(&(bar)[XB_TMO])) break; if (_sp > XB_SPIN_CAP) { atomicAdd(&(bar)[XB_TMO], 1u); break; } } } } while (0)
; __device__ __forceinline__ void xcd_barrier(unsigned* bar, volatile LAS unsigned* st) {
;     ...
;         const unsigned old = xb_add(&bar[XB_XSUB(x)], 1u);
;         const unsigned gen = old / nloc;
;         if (old + 1u == (gen + 1u) * nloc) {
;             __builtin_amdgcn_fence(__ATOMIC_RELEASE, "agent");
;             asm volatile("s_waitcnt vmcnt(0)" ::: "memory");
;             const unsigned og = xb_add(&bar[XB_TOP], 1u);
;             const unsigned tg = og / nx;
;             if (og + 1u == (tg + 1u) * nx) xb_add(&bar[XB_TOPGEN], 1u);
;             else XB_SPIN(xb_ld(&bar[XB_TOPGEN]) == tg, bar);
;             __builtin_amdgcn_fence(__ATOMIC_ACQUIRE, "agent");
;             xb_add(&bar[XB_XGEN(x)], 1u);
;             asm volatile("s_waitcnt vmcnt(0)" ::: "memory");
;         } else {
;             XB_SPIN(xb_ld(&bar[XB_XGEN(x)]) == gen, bar);
.Lmyb0_628:
	s_or_b64 exec, exec, s[14:15]
	v_cvt_f32_u32_e32 v4, v2
	s_waitcnt vmcnt(0)
	v_readfirstlane_b32 s10, v3
	v_sub_u32_e32 v3, 0, v2
	v_rcp_iflag_f32_e32 v4, v4
	v_add_u32_e32 v5, s10, v1
	v_mul_f32_e32 v4, 0x4f7ffffe, v4
	v_cvt_u32_f32_e32 v4, v4
	v_mul_lo_u32 v1, v3, v4
	v_mul_hi_u32 v1, v4, v1
	v_add_u32_e32 v1, v4, v1
	v_mul_hi_u32 v1, v5, v1
	v_mul_lo_u32 v3, v1, v2
	v_sub_u32_e32 v3, v5, v3
	v_add_u32_e32 v4, 1, v1
	v_cmp_ge_u32_e32 vcc, v3, v2
	s_nop 1
	v_cndmask_b32_e32 v1, v1, v4, vcc
	v_sub_u32_e32 v4, v3, v2
	v_cndmask_b32_e32 v3, v3, v4, vcc
	v_add_u32_e32 v4, 1, v1
	v_cmp_ge_u32_e32 vcc, v3, v2
	v_add_u32_e32 v3, 1, v5
	s_nop 0
	v_cndmask_b32_e32 v1, v1, v4, vcc
	v_mul_lo_u32 v4, v2, v1
	v_add_u32_e32 v2, v4, v2
	v_cmp_ne_u32_e32 vcc, v3, v2
	s_and_saveexec_b64 s[12:13], vcc
	s_xor_b64 s[12:13], exec, s[12:13]
	s_cbranch_execz .Lmyb0_642
	s_waitcnt lgkmcnt(0)
	v_add_u32_e32 v6, 6, v3
	v_cmp_eq_u32_e32 vcc, v6, v2
	s_nop 4
	s_cbranch_vccz .Lmy_pf_0
	buffer_wbl2 sc1
.Lmy_pf_0:
	v_mov_b32_e32 v0, 0x2000
	global_load_dword v0, v0, s[6:7] offset:1024 sc1
	s_add_u32 s18, s6, 0x2400
	s_addc_u32 s19, s7, 0
	s_waitcnt vmcnt(0)
	v_cmp_eq_u32_e32 vcc, v0, v1
	s_and_saveexec_b64 s[14:15], vcc
	s_cbranch_execz .Lmyb0_641
	s_add_u32 s16, s4, 0x4200
	s_addc_u32 s17, s5, 0
	s_mov_b32 s10, 1
	s_mov_b64 s[20:21], 0
	s_branch .Lmyb0_632
